# S5 combine phase: grid-stride loop software-pipelined by one iteration (next loads issued before the current arithmetic), trips counted in an SGPR
# speedup vs baseline: 1.0003x; 1.0003x over previous
; __device__ __forceinline__ unsigned pk2(float lo, float hi) { unsigned r; asm("v_cvt_pk_bf16_f32 %0, %1, %2" : "=v"(r) : "v"(lo), "v"(hi)); return r; }
; __device__ __forceinline__ float tanh_fast(float x) { return 1.f - 2.f * __builtin_amdgcn_rcpf(1.f + __expf(2.f * x)); }
;     __device__ __forceinline__ bf16* R(int i) const { return (bf16*)(ws + OFF_R0 + (size_t)i * RSZ); }
; __device__ __forceinline__ void phase_s5_combine(const Fr& F) {
;     const bf16* U = F.R(1); const float* dsk = F.a->in[34];
;     for (size_t i = (size_t)blockIdx.x * NTHR + F.tid; i < (size_t)NT * D / 4; i += (size_t)GRID * NTHR) {
;         const size_t e = i * 4; const int c = (int)(e & 1023);
;         const u32x2 y0 = *(const u32x2*)(F.R(4) + e), y1 = *(const u32x2*)(F.R(5) + e), uw = *(const u32x2*)(U + e); const f32x4 d = *(const f32x4*)(dsk + c);
;         float y[4] = {lo_bf(y0.x) + lo_bf(y1.x) + d.x * lo_bf(uw.x), hi_bf(y0.x) + hi_bf(y1.x) + d.y * hi_bf(uw.x), lo_bf(y0.y) + lo_bf(y1.y) + d.z * lo_bf(uw.y), hi_bf(y0.y) + hi_bf(y1.y) + d.w * hi_bf(uw.y)};
; #pragma unroll
;         for (int k = 0; k < 4; ++k) { const float x = y[k]; y[k] = 0.5f * x * (1.f + tanh_fast(0.7978845608f * (x + 0.044715f * x * x * x))); }
;         u32x2 o; o.x = pk2(y[0], y[1]); o.y = pk2(y[2], y[3]); *(u32x2*)(F.R(0) + e) = o;
;     }
; }
.LBB0_1816:
	s_or_b64 exec, exec, s[6:7]
	v_cmp_gt_i32_e32 vcc, 19, v2
	v_cmp_lt_i32_e64 s[6:7], 18, v3
	s_and_b64 s[6:7], vcc, s[6:7]
	s_and_saveexec_b64 s[8:9], s[6:7]
	s_cbranch_execz .LBB0_1822
	s_mov_b32 s3, 0
	s_lshl_b64 s[6:7], s[2:3], 9
	v_mov_b32_e32 v129, 0
	v_lshl_add_u64 v[0:1], s[6:7], 0, v[128:129]
	s_mov_b64 s[6:7], 0x440000
	v_cmp_gt_u64_e32 vcc, s[6:7], v[0:1]
	s_and_saveexec_b64 s[10:11], vcc
	s_cbranch_execz .LBB0_1821
	s_mov_b32 s6, 0xfffe0000
	s_mov_b32 s7, -1
	v_lshl_add_u64 v[0:1], v[0:1], 0, s[6:7]
	s_lshl_b64 s[6:7], s[2:3], 12
	s_load_dwordx2 s[12:13], s[0:1], 0x110
	s_add_u32 s6, s26, s6
	v_lshlrev_b32_e32 v2, 3, v128
	v_mov_b32_e32 v3, v129
	s_addc_u32 s7, s27, s7
	v_lshl_add_u64 v[2:3], s[6:7], 0, v[2:3]
	s_mov_b64 s[6:7], 0x9a00000
	v_lshl_add_u64 v[2:3], v[2:3], 0, s[6:7]
	s_lshl_b64 s[6:7], s[2:3], 11
	v_lshlrev_b32_e32 v4, 2, v128
	v_mov_b32_e32 v5, v129
	v_lshl_add_u64 v[4:5], s[6:7], 0, v[4:5]
	s_mov_b64 s[14:15], 0
	s_mov_b64 s[16:17], 0x20000
	s_mov_b64 s[18:19], 0x100000
	s_mov_b64 s[20:21], 0x80000
	s_mov_b64 s[22:23], 0x41ffff
	s_mov_b32 s24, 34
	v_add_co_u32_e32 v6, vcc, 0x2200000, v2
	global_load_dwordx2 v[10:11], v[2:3], off
	s_nop 0
	v_addc_co_u32_e32 v7, vcc, 0, v3, vcc
	v_add_co_u32_e32 v12, vcc, 0xf9a00000, v2
	global_load_dwordx2 v[14:15], v[6:7], off
	v_and_b32_e32 v8, 0x3fc, v4
	v_addc_co_u32_e32 v13, vcc, -1, v3, vcc
	v_lshlrev_b32_e32 v18, 2, v8
	global_load_dwordx2 v[16:17], v[12:13], off
	s_waitcnt lgkmcnt(0)
	global_load_dwordx4 v[6:9], v18, s[12:13]
	v_lshl_add_u64 v[0:1], v[0:1], 0, s[16:17]
	v_cmp_lt_u64_e64 s[6:7], s[22:23], v[0:1]
	v_add_co_u32_e32 v12, vcc, 0xf7800000, v2
	v_lshl_add_u64 v[4:5], v[4:5], 0, s[20:21]
	s_or_b64 s[14:15], s[6:7], s[14:15]
	v_addc_co_u32_e32 v13, vcc, -1, v3, vcc
	v_lshl_add_u64 v[2:3], v[2:3], 0, s[18:19]
.LBB0_1819:
	s_waitcnt vmcnt(0)
	v_mov_b32_e32 v110, v10
	v_mov_b32_e32 v111, v11
	v_mov_b32_e32 v114, v14
	v_mov_b32_e32 v115, v15
	v_mov_b32_e32 v116, v16
	v_mov_b32_e32 v117, v17
	v_mov_b32_e32 v106, v6
	v_mov_b32_e32 v107, v7
	v_mov_b32_e32 v108, v8
	v_mov_b32_e32 v109, v9
	v_mov_b32_e32 v112, v12
	v_mov_b32_e32 v113, v13
	s_cmp_eq_u32 s24, 1
	s_cbranch_scc1 .Lcomb_last
	v_add_co_u32_e32 v6, vcc, 0x2200000, v2
	global_load_dwordx2 v[10:11], v[2:3], off
	s_nop 0
	v_addc_co_u32_e32 v7, vcc, 0, v3, vcc
	v_add_co_u32_e32 v12, vcc, 0xf9a00000, v2
	global_load_dwordx2 v[14:15], v[6:7], off
	v_and_b32_e32 v8, 0x3fc, v4
	v_addc_co_u32_e32 v13, vcc, -1, v3, vcc
	v_lshlrev_b32_e32 v18, 2, v8
	global_load_dwordx2 v[16:17], v[12:13], off
	s_waitcnt lgkmcnt(0)
	global_load_dwordx4 v[6:9], v18, s[12:13]
	v_lshl_add_u64 v[0:1], v[0:1], 0, s[16:17]
	v_cmp_lt_u64_e64 s[6:7], s[22:23], v[0:1]
	v_add_co_u32_e32 v12, vcc, 0xf7800000, v2
	v_lshl_add_u64 v[4:5], v[4:5], 0, s[20:21]
	s_or_b64 s[14:15], s[6:7], s[14:15]
	v_addc_co_u32_e32 v13, vcc, -1, v3, vcc
	v_lshl_add_u64 v[2:3], v[2:3], 0, s[18:19]
.Lcomb_last:
	v_lshlrev_b32_e32 v18, 16, v110
	v_and_b32_e32 v110, 0xffff0000, v110
	v_lshlrev_b32_e32 v19, 16, v111
	v_and_b32_e32 v111, 0xffff0000, v111
	v_lshlrev_b32_e32 v20, 16, v114
	v_and_b32_e32 v114, 0xffff0000, v114
	v_lshlrev_b32_e32 v21, 16, v115
	v_and_b32_e32 v115, 0xffff0000, v115
	v_add_f32_e32 v18, v20, v18
	v_lshlrev_b32_e32 v20, 16, v116
	v_add_f32_e32 v110, v114, v110
	v_and_b32_e32 v114, 0xffff0000, v116
	v_add_f32_e32 v116, v21, v19
	v_lshlrev_b32_e32 v19, 16, v117
	v_add_f32_e32 v111, v115, v111
	v_and_b32_e32 v115, 0xffff0000, v117
	v_fmac_f32_e32 v18, v106, v20
	v_fmac_f32_e32 v110, v107, v114
	v_fmac_f32_e32 v116, v108, v19
	v_fmac_f32_e32 v111, v109, v115
	v_mul_f32_e32 v107, 0x3d372713, v18
	v_mul_f32_e32 v109, 0x3d372713, v110
	v_mul_f32_e32 v115, 0x3d372713, v116
	v_mul_f32_e32 v19, 0x3d372713, v111
	v_mul_f32_e32 v107, v18, v107
	v_mul_f32_e32 v109, v110, v109
	v_mul_f32_e32 v106, 0.5, v18
	v_mul_f32_e32 v108, 0.5, v110
	v_mul_f32_e32 v115, v116, v115
	v_mul_f32_e32 v19, v111, v19
	v_fmac_f32_e32 v18, v18, v107
	v_fmac_f32_e32 v110, v110, v109
	v_mul_f32_e32 v114, 0.5, v116
	v_mul_f32_e32 v117, 0.5, v111
	v_fmac_f32_e32 v116, v116, v115
	v_fmac_f32_e32 v111, v111, v19
	v_mul_f32_e32 v107, 0x3f4c422a, v18
	v_mul_f32_e32 v109, 0x3f4c422a, v110
	v_mul_f32_e32 v110, 0x3f4c422a, v116
	v_mul_f32_e32 v111, 0x3f4c422a, v111
	v_add_f32_e32 v107, v107, v107
	v_add_f32_e32 v109, v109, v109
	v_add_f32_e32 v110, v110, v110
	v_add_f32_e32 v111, v111, v111
	v_mul_f32_e32 v107, 0x3fb8aa3b, v107
	v_mul_f32_e32 v109, 0x3fb8aa3b, v109
	v_mul_f32_e32 v110, 0x3fb8aa3b, v110
	v_mul_f32_e32 v111, 0x3fb8aa3b, v111
	v_exp_f32_e32 v107, v107
	v_exp_f32_e32 v109, v109
	v_exp_f32_e32 v110, v110
	v_exp_f32_e32 v111, v111
	v_add_f32_e32 v107, 1.0, v107
	v_add_f32_e32 v109, 1.0, v109
	v_add_f32_e32 v110, 1.0, v110
	v_add_f32_e32 v111, 1.0, v111
	v_rcp_f32_e32 v107, v107
	v_rcp_f32_e32 v109, v109
	v_rcp_f32_e32 v110, v110
	v_rcp_f32_e32 v111, v111
	v_fma_f32 v107, v107, -2.0, 1.0
	v_fma_f32 v109, v109, -2.0, 1.0
	v_fma_f32 v110, v110, -2.0, 1.0
	v_fma_f32 v111, v111, -2.0, 1.0
	v_add_f32_e32 v107, 1.0, v107
	v_add_f32_e32 v109, 1.0, v109
	v_add_f32_e32 v110, 1.0, v110
	v_add_f32_e32 v111, 1.0, v111
	v_mul_f32_e32 v106, v106, v107
	v_mul_f32_e32 v107, v108, v109
	v_mul_f32_e32 v108, v114, v110
	v_mul_f32_e32 v109, v117, v111
	v_cvt_pk_bf16_f32 v106, v106, v107
	v_cvt_pk_bf16_f32 v107, v108, v109
	global_store_dwordx2 v[112:113], v[106:107], off
	s_add_i32 s24, s24, -1
	s_cmp_lg_u32 s24, 0
	s_cbranch_scc1 .LBB0_1819
	s_or_b64 exec, exec, s[14:15]
	v_mov_b32_e32 v2, s34
	v_mov_b32_e32 v3, s35
